# conversion-only workgroups defer their wait on the grid barrier before phases 6 and 14 until after their conversion work (arrival and release unchanged)
# speedup vs baseline: 1.0104x; 1.0040x over previous
.LBB0_644:
	s_mov_b32 s99, 0
	s_cmp_lt_i32 s94, 7
	s_cselect_b64 s[2:3], -1, 0
	s_cmp_gt_i32 s95, 6
	s_cselect_b64 s[0:1], -1, 0
	s_and_b64 s[0:1], s[2:3], s[0:1]
	s_andn2_b64 vcc, exec, s[0:1]
	s_cbranch_vccnz .LBB0_781
	s_andn2_b64 vcc, exec, s[34:35]
	s_cbranch_vccz .LBB0_648
	s_cmp_gt_i32 s47, 63
	s_mov_b64 s[0:1], -1
	s_cbranch_scc1 .LBB0_701

.LBB0_666:
	s_or_b64 exec, exec, s[8:9]
	v_cvt_f32_u32_e32 v5, v3
	s_waitcnt vmcnt(0)
	v_readfirstlane_b32 s6, v4
	v_sub_u32_e32 v4, 0, v3
	v_rcp_iflag_f32_e32 v5, v5
	v_add_u32_e32 v6, s6, v2
	v_mul_f32_e32 v5, 0x4f7ffffe, v5
	v_cvt_u32_f32_e32 v5, v5
	v_mul_lo_u32 v2, v4, v5
	v_mul_hi_u32 v2, v5, v2
	v_add_u32_e32 v2, v5, v2
	v_mul_hi_u32 v2, v6, v2
	v_mul_lo_u32 v4, v2, v3
	v_sub_u32_e32 v4, v6, v4
	v_add_u32_e32 v5, 1, v2
	v_cmp_ge_u32_e32 vcc, v4, v3
	s_nop 1
	v_cndmask_b32_e32 v2, v2, v5, vcc
	v_sub_u32_e32 v5, v4, v3
	v_cndmask_b32_e32 v4, v4, v5, vcc
	v_add_u32_e32 v5, 1, v2
	v_cmp_ge_u32_e32 vcc, v4, v3
	v_add_u32_e32 v4, 1, v6
	s_nop 0
	v_cndmask_b32_e32 v2, v2, v5, vcc
	v_mul_lo_u32 v5, v3, v2
	v_add_u32_e32 v3, v5, v3
	v_cmp_ne_u32_e32 vcc, v4, v3
	s_and_saveexec_b64 s[6:7], vcc
	s_xor_b64 s[6:7], exec, s[6:7]
	s_cbranch_execz .LBB0_680
	s_cmp_gt_i32 s47, 63
	s_cbranch_scc0 .Lbd_normal_0
	v_readfirstlane_b32 s98, v2
	s_mov_b32 s99, 1
	s_branch .LBB0_680
.Lbd_normal_0:
	s_waitcnt lgkmcnt(0)
	v_mov_b32_e32 v1, 0x2000
	global_load_dword v1, v1, s[4:5] offset:1024 sc1
	s_add_u32 s10, s4, 0x2400
	s_addc_u32 s11, s5, 0
	s_waitcnt vmcnt(0)
	v_cmp_eq_u32_e32 vcc, v1, v2
	s_and_saveexec_b64 s[8:9], vcc
	s_cbranch_execz .LBB0_679
	s_mov_b32 s22, 1
	s_mov_b64 s[12:13], 0
	v_mov_b32_e32 v1, 0
	s_branch .LBB0_670

.LBB0_781:
	s_cmp_eq_u32 s99, 1
	s_cbranch_scc0 .Lbd_done_0
	s_mov_b32 s99, 0
	s_mov_b64 s[0:1], exec
	v_readlane_b32 s4, v197, 0
	v_readlane_b32 s5, v197, 1
	s_and_b64 s[4:5], s[0:1], s[4:5]
	s_mov_b64 exec, s[4:5]
	s_cbranch_execz .Lbd_rest_0
	v_readlane_b32 s4, v197, 50
	s_lshl_b32 s4, s4, 8
	s_add_u32 s4, s92, s4
	s_addc_u32 s5, s93, 0
	s_add_u32 s4, s4, 0x2400
	s_addc_u32 s5, s5, 0
	v_mov_b32_e32 v1, 0
	v_mov_b32_e32 v2, s98
.Lbd_spin_0:
	global_load_dword v3, v1, s[4:5] sc1
	s_waitcnt vmcnt(0)
	v_cmp_ne_u32_e32 vcc, v3, v2
	s_cbranch_vccnz .Lbd_out_0
	s_sleep 1
	s_branch .Lbd_spin_0

.Lbd_rest_0:
	s_mov_b64 exec, s[0:1]

.LBB0_1233:
	s_mov_b32 s99, 0
	s_cmp_lt_i32 s94, 15
	s_cselect_b64 s[40:41], -1, 0
	s_cmp_gt_i32 s95, 14
	s_cselect_b64 s[0:1], -1, 0
	s_and_b64 s[0:1], s[40:41], s[0:1]
	s_andn2_b64 vcc, exec, s[0:1]
	s_cbranch_vccnz .LBB0_1378
	s_andn2_b64 vcc, exec, s[2:3]
	s_cbranch_vccz .LBB0_1237
	s_cmp_gt_i32 s47, 63
	s_mov_b64 s[0:1], -1
	s_cbranch_scc1 .LBB0_1290

.LBB0_1255:
	s_or_b64 exec, exec, s[6:7]
	v_cvt_f32_u32_e32 v5, v3
	s_waitcnt vmcnt(0)
	v_readfirstlane_b32 s4, v4
	v_sub_u32_e32 v4, 0, v3
	v_rcp_iflag_f32_e32 v5, v5
	v_add_u32_e32 v6, s4, v2
	v_mul_f32_e32 v5, 0x4f7ffffe, v5
	v_cvt_u32_f32_e32 v5, v5
	v_mul_lo_u32 v2, v4, v5
	v_mul_hi_u32 v2, v5, v2
	v_add_u32_e32 v2, v5, v2
	v_mul_hi_u32 v2, v6, v2
	v_mul_lo_u32 v4, v2, v3
	v_sub_u32_e32 v4, v6, v4
	v_add_u32_e32 v5, 1, v2
	v_cmp_ge_u32_e32 vcc, v4, v3
	s_nop 1
	v_cndmask_b32_e32 v2, v2, v5, vcc
	v_sub_u32_e32 v5, v4, v3
	v_cndmask_b32_e32 v4, v4, v5, vcc
	v_add_u32_e32 v5, 1, v2
	v_cmp_ge_u32_e32 vcc, v4, v3
	v_add_u32_e32 v4, 1, v6
	s_nop 0
	v_cndmask_b32_e32 v2, v2, v5, vcc
	v_mul_lo_u32 v5, v3, v2
	v_add_u32_e32 v3, v5, v3
	v_cmp_ne_u32_e32 vcc, v4, v3
	s_and_saveexec_b64 s[4:5], vcc
	s_xor_b64 s[4:5], exec, s[4:5]
	s_cbranch_execz .LBB0_1269
	s_cmp_gt_i32 s47, 63
	s_cbranch_scc0 .Lbd_normal_1
	v_readfirstlane_b32 s98, v2
	s_mov_b32 s99, 1
	s_branch .LBB0_1269
.Lbd_normal_1:
	s_waitcnt lgkmcnt(0)
	v_mov_b32_e32 v1, 0x2000
	global_load_dword v1, v1, s[2:3] offset:1024 sc1
	s_add_u32 s8, s2, 0x2400
	s_addc_u32 s9, s3, 0
	s_waitcnt vmcnt(0)
	v_cmp_eq_u32_e32 vcc, v1, v2
	s_and_saveexec_b64 s[6:7], vcc
	s_cbranch_execz .LBB0_1268
	s_mov_b32 s20, 1
	s_mov_b64 s[10:11], 0
	v_mov_b32_e32 v1, 0
	s_branch .LBB0_1259

.LBB0_1378:
	s_cmp_eq_u32 s99, 1
	s_cbranch_scc0 .Lbd_done_1
	s_mov_b32 s99, 0
	s_mov_b64 s[0:1], exec
	v_readlane_b32 s2, v197, 0
	v_readlane_b32 s3, v197, 1
	s_and_b64 s[2:3], s[0:1], s[2:3]
	s_mov_b64 exec, s[2:3]
	s_cbranch_execz .Lbd_rest_1
	v_readlane_b32 s2, v197, 50
	s_lshl_b32 s2, s2, 8
	s_add_u32 s2, s92, s2
	s_addc_u32 s3, s93, 0
	s_add_u32 s2, s2, 0x2400
	s_addc_u32 s3, s3, 0
	v_mov_b32_e32 v1, 0
	v_mov_b32_e32 v2, s98
.Lbd_spin_1:
	global_load_dword v3, v1, s[2:3] sc1
	s_waitcnt vmcnt(0)
	v_cmp_ne_u32_e32 vcc, v3, v2
	s_cbranch_vccnz .Lbd_out_1
	s_sleep 1
	s_branch .Lbd_spin_1
